# RG-LRU task prologue: batch the 63 serialized wB weight load pairs (3-6 round trips instead of 63)
# speedup vs baseline: 1.0037x; 1.0037x over previous
.LBB0_200:
	s_or_b64 exec, exec, s[80:81]
	v_readfirstlane_b32 s1, v0
	s_cmpk_gt_u32 s1, 0x7ff
	s_mov_b64 s[80:81], -1
	s_cbranch_scc1 .LBB0_195
	s_bfe_u32 s0, s1, 0x30005
	s_lshl_b32 s20, s0, 8
	v_lshl_add_u64 v[24:25], v[144:145], 0, s[20:21]
	v_lshl_add_u64 v[20:21], v[146:147], 0, s[20:21]
	s_lshl_b32 s20, s0, 14
	v_lshl_add_u64 v[44:45], v[148:149], 0, s[20:21]
	v_mov_b32_e32 v161, v99
	v_lshl_add_u64 v[68:69], v[44:45], 0, v[160:161]
	global_load_dword v40, v[68:69], off offset:256
	global_load_dword v41, v[68:69], off
	global_load_dwordx4 v[0:3], v[24:25], off offset:16
	global_load_dwordx4 v[4:7], v[24:25], off
	global_load_dwordx4 v[8:11], v[24:25], off offset:2064
	global_load_dwordx4 v[12:15], v[24:25], off offset:2048
	v_add_co_u32_e32 v32, vcc, 0x1000, v24
	s_mov_b64 s[22:23], 0x1800
	v_lshl_add_u64 v[28:29], v[24:25], 0, s[54:55]
	v_lshl_add_u64 v[36:37], v[24:25], 0, s[22:23]
	v_addc_co_u32_e32 v33, vcc, 0, v25, vcc
	global_load_dwordx4 v[16:19], v[20:21], off offset:16
	s_nop 0
	global_load_dwordx4 v[20:23], v[20:21], off
	s_nop 0
	global_load_dwordx4 v[24:27], v[32:33], off
	s_nop 0
	global_load_dwordx4 v[28:31], v[28:29], off offset:16
	s_nop 0
	global_load_dwordx4 v[32:35], v[32:33], off offset:2048
	s_nop 0
	global_load_dwordx4 v[36:39], v[36:37], off offset:16
	v_mov_b32_e32 v163, v99
	v_lshl_add_u64 v[72:73], v[44:45], 0, v[162:163]
	v_lshl_add_u64 v[76:77], v[150:151], 0, s[20:21]
	v_lshl_add_u64 v[104:105], v[76:77], 0, v[160:161]
	s_waitcnt vmcnt(0)
	v_lshl_add_u64 v[108:109], v[76:77], 0, v[162:163]
	s_lshl_b32 s26, s0, 6
	s_lshr_b32 s23, s1, 8
	s_lshl_b32 s1, s1, 7
	s_and_b32 s22, s1, 0xf80
	s_lshl_b32 s1, s23, 12
	s_or_b32 s20, s22, s1
	s_add_u32 s80, s20, -3
	s_addc_u32 s81, 0, -1
	v_cmp_gt_i32_e32 vcc, s22, v172
	v_mov_b32_e32 v110, v99
	v_mov_b32_e32 v111, v99
	s_waitcnt vmcnt(10)
	v_cvt_pk_bf16_f32 v40, v41, v40
	global_load_dword v41, v[68:69], off offset:768
	global_load_dword v234, v[68:69], off offset:512
	global_load_dword v42, v[68:69], off offset:1280
	global_load_dword v235, v[68:69], off offset:1024
	global_load_dword v43, v[68:69], off offset:1792
	global_load_dword v236, v[68:69], off offset:1536
	global_load_dword v44, v[72:73], off offset:256
	global_load_dword v237, v[72:73], off
	global_load_dword v45, v[72:73], off offset:768
	global_load_dword v238, v[72:73], off offset:512
	global_load_dword v46, v[72:73], off offset:1280
	global_load_dword v239, v[72:73], off offset:1024
	global_load_dword v47, v[72:73], off offset:1792
	global_load_dword v240, v[72:73], off offset:1536
	global_load_dword v48, v[68:69], off offset:320
	global_load_dword v241, v[68:69], off offset:64
	global_load_dword v49, v[68:69], off offset:832
	global_load_dword v242, v[68:69], off offset:576
	global_load_dword v50, v[68:69], off offset:1344
	global_load_dword v243, v[68:69], off offset:1088
	global_load_dword v51, v[68:69], off offset:1856
	global_load_dword v244, v[68:69], off offset:1600
	global_load_dword v52, v[72:73], off offset:320
	global_load_dword v245, v[72:73], off offset:64
	global_load_dword v53, v[72:73], off offset:832
	global_load_dword v246, v[72:73], off offset:576
	global_load_dword v54, v[72:73], off offset:1344
	global_load_dword v247, v[72:73], off offset:1088
	global_load_dword v55, v[72:73], off offset:1856
	global_load_dword v248, v[72:73], off offset:1600
	global_load_dword v56, v[68:69], off offset:384
	global_load_dword v249, v[68:69], off offset:128
	global_load_dword v57, v[68:69], off offset:896
	global_load_dword v250, v[68:69], off offset:640
	global_load_dword v58, v[68:69], off offset:1408
	global_load_dword v251, v[68:69], off offset:1152
	global_load_dword v59, v[68:69], off offset:1920
	global_load_dword v252, v[68:69], off offset:1664
	global_load_dword v60, v[72:73], off offset:384
	global_load_dword v253, v[72:73], off offset:128
	s_waitcnt vmcnt(0)
	v_cvt_pk_bf16_f32 v41, v234, v41
	v_cvt_pk_bf16_f32 v42, v235, v42
	v_cvt_pk_bf16_f32 v43, v236, v43
	v_cvt_pk_bf16_f32 v44, v237, v44
	v_cvt_pk_bf16_f32 v45, v238, v45
	v_cvt_pk_bf16_f32 v46, v239, v46
	v_cvt_pk_bf16_f32 v47, v240, v47
	v_cvt_pk_bf16_f32 v48, v241, v48
	v_cvt_pk_bf16_f32 v49, v242, v49
	v_cvt_pk_bf16_f32 v50, v243, v50
	v_cvt_pk_bf16_f32 v51, v244, v51
	v_cvt_pk_bf16_f32 v52, v245, v52
	v_cvt_pk_bf16_f32 v53, v246, v53
	v_cvt_pk_bf16_f32 v54, v247, v54
	v_cvt_pk_bf16_f32 v55, v248, v55
	v_cvt_pk_bf16_f32 v56, v249, v56
	v_cvt_pk_bf16_f32 v57, v250, v57
	v_cvt_pk_bf16_f32 v58, v251, v58
	v_cvt_pk_bf16_f32 v59, v252, v59
	v_cvt_pk_bf16_f32 v60, v253, v60
	global_load_dword v61, v[72:73], off offset:896
	global_load_dword v234, v[72:73], off offset:640
	global_load_dword v62, v[72:73], off offset:1408
	global_load_dword v235, v[72:73], off offset:1152
	global_load_dword v63, v[72:73], off offset:1920
	global_load_dword v236, v[72:73], off offset:1664
	global_load_dword v64, v[68:69], off offset:448
	global_load_dword v237, v[68:69], off offset:192
	global_load_dword v65, v[68:69], off offset:960
	global_load_dword v238, v[68:69], off offset:704
	global_load_dword v66, v[68:69], off offset:1472
	global_load_dword v239, v[68:69], off offset:1216
	global_load_dword v67, v[68:69], off offset:1984
	s_nop 0
	global_load_dword v240, v[68:69], off offset:1728
	global_load_dword v68, v[72:73], off offset:448
	global_load_dword v241, v[72:73], off offset:192
	global_load_dword v69, v[72:73], off offset:960
	global_load_dword v242, v[72:73], off offset:704
	global_load_dword v70, v[72:73], off offset:1472
	global_load_dword v243, v[72:73], off offset:1216
	global_load_dword v71, v[72:73], off offset:1984
	s_nop 0
	global_load_dword v244, v[72:73], off offset:1728
	global_load_dword v72, v[104:105], off offset:256
	global_load_dword v245, v[104:105], off
	global_load_dword v73, v[104:105], off offset:768
	global_load_dword v246, v[104:105], off offset:512
	global_load_dword v74, v[104:105], off offset:1280
	global_load_dword v247, v[104:105], off offset:1024
	global_load_dword v75, v[104:105], off offset:1792
	global_load_dword v248, v[104:105], off offset:1536
	global_load_dword v76, v[108:109], off offset:256
	global_load_dword v249, v[108:109], off
	global_load_dword v77, v[108:109], off offset:768
	global_load_dword v250, v[108:109], off offset:512
	global_load_dword v78, v[108:109], off offset:1280
	global_load_dword v251, v[108:109], off offset:1024
	global_load_dword v79, v[108:109], off offset:1792
	global_load_dword v252, v[108:109], off offset:1536
	global_load_dword v80, v[104:105], off offset:320
	global_load_dword v253, v[104:105], off offset:64
	s_waitcnt vmcnt(0)
	v_cvt_pk_bf16_f32 v61, v234, v61
	v_cvt_pk_bf16_f32 v62, v235, v62
	v_cvt_pk_bf16_f32 v63, v236, v63
	v_cvt_pk_bf16_f32 v64, v237, v64
	v_cvt_pk_bf16_f32 v65, v238, v65
	v_cvt_pk_bf16_f32 v66, v239, v66
	v_cvt_pk_bf16_f32 v67, v240, v67
	v_cvt_pk_bf16_f32 v68, v241, v68
	v_cvt_pk_bf16_f32 v69, v242, v69
	v_cvt_pk_bf16_f32 v70, v243, v70
	v_cvt_pk_bf16_f32 v71, v244, v71
	v_cvt_pk_bf16_f32 v72, v245, v72
	v_cvt_pk_bf16_f32 v73, v246, v73
	v_cvt_pk_bf16_f32 v74, v247, v74
	v_cvt_pk_bf16_f32 v75, v248, v75
	v_cvt_pk_bf16_f32 v76, v249, v76
	v_cvt_pk_bf16_f32 v77, v250, v77
	v_cvt_pk_bf16_f32 v78, v251, v78
	v_cvt_pk_bf16_f32 v79, v252, v79
	v_cvt_pk_bf16_f32 v80, v253, v80
	global_load_dword v81, v[104:105], off offset:832
	global_load_dword v234, v[104:105], off offset:576
	global_load_dword v82, v[104:105], off offset:1344
	global_load_dword v235, v[104:105], off offset:1088
	global_load_dword v83, v[104:105], off offset:1856
	global_load_dword v236, v[104:105], off offset:1600
	global_load_dword v84, v[108:109], off offset:320
	global_load_dword v237, v[108:109], off offset:64
	global_load_dword v85, v[108:109], off offset:832
	global_load_dword v238, v[108:109], off offset:576
	global_load_dword v86, v[108:109], off offset:1344
	global_load_dword v239, v[108:109], off offset:1088
	global_load_dword v87, v[108:109], off offset:1856
	global_load_dword v240, v[108:109], off offset:1600
	global_load_dword v88, v[104:105], off offset:384
	global_load_dword v241, v[104:105], off offset:128
	global_load_dword v89, v[104:105], off offset:896
	global_load_dword v242, v[104:105], off offset:640
	global_load_dword v90, v[104:105], off offset:1408
	global_load_dword v243, v[104:105], off offset:1152
	global_load_dword v91, v[104:105], off offset:1920
	global_load_dword v244, v[104:105], off offset:1664
	global_load_dword v92, v[108:109], off offset:384
	global_load_dword v245, v[108:109], off offset:128
	global_load_dword v93, v[108:109], off offset:896
	global_load_dword v246, v[108:109], off offset:640
	global_load_dword v94, v[108:109], off offset:1408
	global_load_dword v247, v[108:109], off offset:1152
	global_load_dword v95, v[108:109], off offset:1920
	global_load_dword v248, v[108:109], off offset:1664
	global_load_dword v249, v[104:105], off offset:448
	global_load_dword v100, v[104:105], off offset:192
	global_load_dword v250, v[104:105], off offset:960
	global_load_dword v101, v[104:105], off offset:704
	global_load_dword v251, v[104:105], off offset:1472
	global_load_dword v102, v[104:105], off offset:1216
	global_load_dword v252, v[104:105], off offset:1984
	global_load_dword v103, v[104:105], off offset:1728
	global_load_dword v253, v[108:109], off offset:448
	global_load_dword v104, v[108:109], off offset:192
	s_waitcnt vmcnt(0)
	v_cvt_pk_bf16_f32 v81, v234, v81
	v_cvt_pk_bf16_f32 v82, v235, v82
	v_cvt_pk_bf16_f32 v83, v236, v83
	v_cvt_pk_bf16_f32 v84, v237, v84
	v_cvt_pk_bf16_f32 v85, v238, v85
	v_cvt_pk_bf16_f32 v86, v239, v86
	v_cvt_pk_bf16_f32 v87, v240, v87
	v_cvt_pk_bf16_f32 v88, v241, v88
	v_cvt_pk_bf16_f32 v89, v242, v89
	v_cvt_pk_bf16_f32 v90, v243, v90
	v_cvt_pk_bf16_f32 v91, v244, v91
	v_cvt_pk_bf16_f32 v92, v245, v92
	v_cvt_pk_bf16_f32 v93, v246, v93
	v_cvt_pk_bf16_f32 v94, v247, v94
	v_cvt_pk_bf16_f32 v95, v248, v95
	v_cvt_pk_bf16_f32 v100, v100, v249
	v_cvt_pk_bf16_f32 v101, v101, v250
	v_cvt_pk_bf16_f32 v102, v102, v251
	v_cvt_pk_bf16_f32 v103, v103, v252
	v_cvt_pk_bf16_f32 v104, v104, v253
	global_load_dword v234, v[108:109], off offset:960
	global_load_dword v105, v[108:109], off offset:704
	global_load_dword v235, v[108:109], off offset:1472
	global_load_dword v106, v[108:109], off offset:1216
	global_load_dword v236, v[108:109], off offset:1984
	global_load_dword v107, v[108:109], off offset:1728
	v_or_b32_e32 v108, s26, v97
	v_lshlrev_b32_e32 v108, 2, v108
	v_mov_b32_e32 v109, v99
	s_waitcnt vmcnt(0)
	v_cvt_pk_bf16_f32 v105, v105, v234
	v_cvt_pk_bf16_f32 v106, v106, v235
	v_cvt_pk_bf16_f32 v107, v107, v236
	global_load_dword v161, v108, s[74:75]
	global_load_dword v163, v108, s[76:77]
	global_load_dword v181, v108, s[74:75] offset:64
	global_load_dword v188, v108, s[76:77] offset:64
	global_load_dword v189, v108, s[74:75] offset:128
	global_load_dword v190, v108, s[76:77] offset:128
	global_load_dword v191, v108, s[76:77] offset:192
	global_load_dword v192, v108, s[74:75] offset:192
	global_load_dword v123, v108, s[78:79]
	global_load_dword v122, v108, s[78:79] offset:64
	global_load_dword v121, v108, s[78:79] offset:128
	global_load_dword v120, v108, s[78:79] offset:192
	v_mov_b32_e32 v108, v99
	v_lshlrev_b32_e32 v98, 1, v96
	s_and_saveexec_b64 s[82:83], vcc
	s_cbranch_execz .LBB0_203
	v_lshl_add_u64 v[108:109], s[80:81], 0, v[152:153]
	v_mov_b64_e32 v[110:111], s[16:17]
	v_mad_u64_u32 v[110:111], s[42:43], v108, s99, v[110:111]
	v_mad_i32_i24 v111, v109, s99, v111
	s_lshl_b32 s20, s26, 1
	v_lshl_add_u64 v[108:109], v[110:111], 0, s[20:21]
	v_lshl_add_u64 v[108:109], v[108:109], 0, v[98:99]
	global_load_dwordx4 v[108:111], v[108:109], off offset:3072

.LBB0_250:
	s_bfe_u32 s0, s23, 0x30005
	s_lshl_b32 s20, s0, 8
	v_lshl_add_u64 v[24:25], v[96:97], 0, s[20:21]
	v_lshl_add_u64 v[20:21], v[152:153], 0, s[20:21]
	s_lshl_b32 s20, s0, 14
	v_lshl_add_u64 v[44:45], v[154:155], 0, s[20:21]
	v_mov_b32_e32 v173, v99
	v_lshl_add_u64 v[68:69], v[44:45], 0, v[172:173]
	global_load_dword v40, v[68:69], off offset:256
	global_load_dword v41, v[68:69], off
	global_load_dwordx4 v[0:3], v[24:25], off offset:16
	global_load_dwordx4 v[4:7], v[24:25], off
	global_load_dwordx4 v[8:11], v[24:25], off offset:2064
	global_load_dwordx4 v[12:15], v[24:25], off offset:2048
	v_add_co_u32_e32 v32, vcc, 0x1000, v24
	s_mov_b64 s[26:27], 0x1800
	v_lshl_add_u64 v[28:29], v[24:25], 0, s[54:55]
	v_lshl_add_u64 v[36:37], v[24:25], 0, s[26:27]
	v_addc_co_u32_e32 v33, vcc, 0, v25, vcc
	global_load_dwordx4 v[16:19], v[20:21], off offset:16
	s_nop 0
	global_load_dwordx4 v[20:23], v[20:21], off
	s_nop 0
	global_load_dwordx4 v[24:27], v[32:33], off
	s_nop 0
	global_load_dwordx4 v[28:31], v[28:29], off offset:16
	s_nop 0
	global_load_dwordx4 v[32:35], v[32:33], off offset:2048
	s_nop 0
	global_load_dwordx4 v[36:39], v[36:37], off offset:16
	v_mov_b32_e32 v175, v99
	v_lshl_add_u64 v[72:73], v[44:45], 0, v[174:175]
	v_lshl_add_u64 v[76:77], v[156:157], 0, s[20:21]
	v_lshl_add_u64 v[104:105], v[76:77], 0, v[172:173]
	s_waitcnt vmcnt(0)
	v_lshl_add_u64 v[108:109], v[76:77], 0, v[174:175]
	s_lshl_b32 s1, s0, 6
	s_lshr_b32 s0, s23, 5
	s_ashr_i32 s72, s23, 8
	s_and_b32 s20, s23, 31
	s_cmp_eq_u32 s20, 0
	v_cvt_pk_bf16_f32 v40, v41, v40
	global_load_dword v41, v[68:69], off offset:768
	global_load_dword v252, v[68:69], off offset:512
	global_load_dword v42, v[68:69], off offset:1280
	global_load_dword v253, v[68:69], off offset:1024
	global_load_dword v43, v[68:69], off offset:1792
	global_load_dword v230, v[68:69], off offset:1536
	global_load_dword v44, v[72:73], off offset:256
	global_load_dword v231, v[72:73], off
	global_load_dword v45, v[72:73], off offset:768
	global_load_dword v232, v[72:73], off offset:512
	global_load_dword v46, v[72:73], off offset:1280
	global_load_dword v233, v[72:73], off offset:1024
	global_load_dword v47, v[72:73], off offset:1792
	global_load_dword v234, v[72:73], off offset:1536
	global_load_dword v48, v[68:69], off offset:320
	global_load_dword v235, v[68:69], off offset:64
	global_load_dword v49, v[68:69], off offset:832
	global_load_dword v120, v[68:69], off offset:576
	global_load_dword v50, v[68:69], off offset:1344
	global_load_dword v121, v[68:69], off offset:1088
	global_load_dword v51, v[68:69], off offset:1856
	global_load_dword v122, v[68:69], off offset:1600
	global_load_dword v52, v[72:73], off offset:320
	global_load_dword v123, v[72:73], off offset:64
	s_waitcnt vmcnt(0)
	v_cvt_pk_bf16_f32 v41, v252, v41
	v_cvt_pk_bf16_f32 v42, v253, v42
	v_cvt_pk_bf16_f32 v43, v230, v43
	v_cvt_pk_bf16_f32 v44, v231, v44
	v_cvt_pk_bf16_f32 v45, v232, v45
	v_cvt_pk_bf16_f32 v46, v233, v46
	v_cvt_pk_bf16_f32 v47, v234, v47
	v_cvt_pk_bf16_f32 v48, v235, v48
	v_cvt_pk_bf16_f32 v49, v120, v49
	v_cvt_pk_bf16_f32 v50, v121, v50
	v_cvt_pk_bf16_f32 v51, v122, v51
	v_cvt_pk_bf16_f32 v52, v123, v52
	global_load_dword v53, v[72:73], off offset:832
	global_load_dword v252, v[72:73], off offset:576
	global_load_dword v54, v[72:73], off offset:1344
	global_load_dword v253, v[72:73], off offset:1088
	global_load_dword v55, v[72:73], off offset:1856
	global_load_dword v230, v[72:73], off offset:1600
	global_load_dword v56, v[68:69], off offset:384
	global_load_dword v231, v[68:69], off offset:128
	global_load_dword v57, v[68:69], off offset:896
	global_load_dword v232, v[68:69], off offset:640
	global_load_dword v58, v[68:69], off offset:1408
	global_load_dword v233, v[68:69], off offset:1152
	global_load_dword v59, v[68:69], off offset:1920
	global_load_dword v234, v[68:69], off offset:1664
	global_load_dword v60, v[72:73], off offset:384
	global_load_dword v235, v[72:73], off offset:128
	global_load_dword v61, v[72:73], off offset:896
	global_load_dword v120, v[72:73], off offset:640
	global_load_dword v62, v[72:73], off offset:1408
	global_load_dword v121, v[72:73], off offset:1152
	global_load_dword v63, v[72:73], off offset:1920
	global_load_dword v122, v[72:73], off offset:1664
	global_load_dword v64, v[68:69], off offset:448
	global_load_dword v123, v[68:69], off offset:192
	s_waitcnt vmcnt(0)
	v_cvt_pk_bf16_f32 v53, v252, v53
	v_cvt_pk_bf16_f32 v54, v253, v54
	v_cvt_pk_bf16_f32 v55, v230, v55
	v_cvt_pk_bf16_f32 v56, v231, v56
	v_cvt_pk_bf16_f32 v57, v232, v57
	v_cvt_pk_bf16_f32 v58, v233, v58
	v_cvt_pk_bf16_f32 v59, v234, v59
	v_cvt_pk_bf16_f32 v60, v235, v60
	v_cvt_pk_bf16_f32 v61, v120, v61
	v_cvt_pk_bf16_f32 v62, v121, v62
	v_cvt_pk_bf16_f32 v63, v122, v63
	v_cvt_pk_bf16_f32 v64, v123, v64
	global_load_dword v65, v[68:69], off offset:960
	global_load_dword v252, v[68:69], off offset:704
	global_load_dword v66, v[68:69], off offset:1472
	global_load_dword v253, v[68:69], off offset:1216
	global_load_dword v67, v[68:69], off offset:1984
	s_nop 0
	global_load_dword v230, v[68:69], off offset:1728
	global_load_dword v68, v[72:73], off offset:448
	global_load_dword v231, v[72:73], off offset:192
	global_load_dword v69, v[72:73], off offset:960
	global_load_dword v232, v[72:73], off offset:704
	global_load_dword v70, v[72:73], off offset:1472
	global_load_dword v233, v[72:73], off offset:1216
	global_load_dword v71, v[72:73], off offset:1984
	s_nop 0
	global_load_dword v234, v[72:73], off offset:1728
	global_load_dword v72, v[104:105], off offset:256
	global_load_dword v235, v[104:105], off
	global_load_dword v73, v[104:105], off offset:768
	global_load_dword v120, v[104:105], off offset:512
	global_load_dword v74, v[104:105], off offset:1280
	global_load_dword v121, v[104:105], off offset:1024
	global_load_dword v75, v[104:105], off offset:1792
	global_load_dword v122, v[104:105], off offset:1536
	global_load_dword v76, v[108:109], off offset:256
	global_load_dword v123, v[108:109], off
	s_waitcnt vmcnt(0)
	v_cvt_pk_bf16_f32 v65, v252, v65
	v_cvt_pk_bf16_f32 v66, v253, v66
	v_cvt_pk_bf16_f32 v67, v230, v67
	v_cvt_pk_bf16_f32 v68, v231, v68
	v_cvt_pk_bf16_f32 v69, v232, v69
	v_cvt_pk_bf16_f32 v70, v233, v70
	v_cvt_pk_bf16_f32 v71, v234, v71
	v_cvt_pk_bf16_f32 v72, v235, v72
	v_cvt_pk_bf16_f32 v73, v120, v73
	v_cvt_pk_bf16_f32 v74, v121, v74
	v_cvt_pk_bf16_f32 v75, v122, v75
	v_cvt_pk_bf16_f32 v76, v123, v76
	global_load_dword v77, v[108:109], off offset:768
	global_load_dword v252, v[108:109], off offset:512
	global_load_dword v78, v[108:109], off offset:1280
	global_load_dword v253, v[108:109], off offset:1024
	global_load_dword v79, v[108:109], off offset:1792
	global_load_dword v230, v[108:109], off offset:1536
	global_load_dword v80, v[104:105], off offset:320
	global_load_dword v231, v[104:105], off offset:64
	global_load_dword v81, v[104:105], off offset:832
	global_load_dword v232, v[104:105], off offset:576
	global_load_dword v82, v[104:105], off offset:1344
	global_load_dword v233, v[104:105], off offset:1088
	global_load_dword v83, v[104:105], off offset:1856
	global_load_dword v234, v[104:105], off offset:1600
	global_load_dword v84, v[108:109], off offset:320
	global_load_dword v235, v[108:109], off offset:64
	global_load_dword v85, v[108:109], off offset:832
	global_load_dword v120, v[108:109], off offset:576
	global_load_dword v86, v[108:109], off offset:1344
	global_load_dword v121, v[108:109], off offset:1088
	global_load_dword v87, v[108:109], off offset:1856
	global_load_dword v122, v[108:109], off offset:1600
	global_load_dword v88, v[104:105], off offset:384
	global_load_dword v123, v[104:105], off offset:128
	s_waitcnt vmcnt(0)
	v_cvt_pk_bf16_f32 v77, v252, v77
	v_cvt_pk_bf16_f32 v78, v253, v78
	v_cvt_pk_bf16_f32 v79, v230, v79
	v_cvt_pk_bf16_f32 v80, v231, v80
	v_cvt_pk_bf16_f32 v81, v232, v81
	v_cvt_pk_bf16_f32 v82, v233, v82
	v_cvt_pk_bf16_f32 v83, v234, v83
	v_cvt_pk_bf16_f32 v84, v235, v84
	v_cvt_pk_bf16_f32 v85, v120, v85
	v_cvt_pk_bf16_f32 v86, v121, v86
	v_cvt_pk_bf16_f32 v87, v122, v87
	v_cvt_pk_bf16_f32 v88, v123, v88
	global_load_dword v89, v[104:105], off offset:896
	global_load_dword v252, v[104:105], off offset:640
	global_load_dword v90, v[104:105], off offset:1408
	global_load_dword v253, v[104:105], off offset:1152
	global_load_dword v91, v[104:105], off offset:1920
	global_load_dword v230, v[104:105], off offset:1664
	global_load_dword v92, v[108:109], off offset:384
	global_load_dword v231, v[108:109], off offset:128
	global_load_dword v93, v[108:109], off offset:896
	global_load_dword v232, v[108:109], off offset:640
	global_load_dword v94, v[108:109], off offset:1408
	global_load_dword v233, v[108:109], off offset:1152
	global_load_dword v95, v[108:109], off offset:1920
	global_load_dword v234, v[108:109], off offset:1664
	global_load_dword v100, v[104:105], off offset:448
	global_load_dword v235, v[104:105], off offset:192
	global_load_dword v101, v[104:105], off offset:960
	global_load_dword v120, v[104:105], off offset:704
	global_load_dword v102, v[104:105], off offset:1472
	global_load_dword v121, v[104:105], off offset:1216
	global_load_dword v103, v[104:105], off offset:1984
	s_nop 0
	global_load_dword v122, v[104:105], off offset:1728
	global_load_dword v104, v[108:109], off offset:448
	global_load_dword v123, v[108:109], off offset:192
	s_waitcnt vmcnt(0)
	v_cvt_pk_bf16_f32 v89, v252, v89
	v_cvt_pk_bf16_f32 v90, v253, v90
	v_cvt_pk_bf16_f32 v91, v230, v91
	v_cvt_pk_bf16_f32 v92, v231, v92
	v_cvt_pk_bf16_f32 v93, v232, v93
	v_cvt_pk_bf16_f32 v94, v233, v94
	v_cvt_pk_bf16_f32 v95, v234, v95
	v_cvt_pk_bf16_f32 v100, v235, v100
	v_cvt_pk_bf16_f32 v101, v120, v101
	v_cvt_pk_bf16_f32 v102, v121, v102
	v_cvt_pk_bf16_f32 v103, v122, v103
	v_cvt_pk_bf16_f32 v104, v123, v104
	global_load_dword v105, v[108:109], off offset:960
	global_load_dword v252, v[108:109], off offset:704
	global_load_dword v106, v[108:109], off offset:1472
	global_load_dword v253, v[108:109], off offset:1216
	global_load_dword v107, v[108:109], off offset:1984
	s_nop 0
	global_load_dword v230, v[108:109], off offset:1728
	v_or_b32_e32 v109, s1, v220
	v_lshlrev_b32_e32 v109, 2, v109
	s_waitcnt vmcnt(0)
	v_cvt_pk_bf16_f32 v105, v252, v105
	v_cvt_pk_bf16_f32 v106, v253, v106
	v_cvt_pk_bf16_f32 v107, v230, v107
	global_load_dword v173, v109, s[8:9]
	global_load_dword v175, v109, s[68:69]
	global_load_dword v230, v109, s[8:9] offset:64
	global_load_dword v231, v109, s[68:69] offset:64
	global_load_dword v232, v109, s[8:9] offset:128
	global_load_dword v233, v109, s[68:69] offset:128
	global_load_dword v234, v109, s[68:69] offset:192
	global_load_dword v235, v109, s[8:9] offset:192
	global_load_dword v123, v109, s[70:71]
	global_load_dword v122, v109, s[70:71] offset:64
	global_load_dword v121, v109, s[70:71] offset:128
	global_load_dword v120, v109, s[70:71] offset:192
	s_cbranch_scc1 .LBB0_267
	s_and_b32 s26, s0, 7
	s_lshl_b32 s27, s72, 3
	s_or_b32 s26, s27, s26
	s_ashr_i32 s27, s26, 31
	s_lshl_b64 s[26:27], s[26:27], 14
	v_lshl_add_u64 v[108:109], v[164:165], 0, s[26:27]
	s_mov_b32 s26, 0
	v_mov_b32_e32 v177, 0
	s_branch .LBB0_253
